# v14 + LayerNorm loop (2nd instance): next-row wait moved in front of the row's last stores, no drain at the loop top
# speedup vs baseline: 1.0072x; 1.0004x over previous
; DI void lnmod_phase(const Args& A, LAS unsigned char* lds, int tid, int bid, int G, bool init, int l_norm, int i_norm, int l_mod, int i_mod, bool want_dt, int nrows, bool ctx_partial, const float* gprev, const float* bprev) {
;     ...
;     f32x4 g[4], bb[4];
;     if (l_norm >= 0) {
; #pragma unroll
;         for (int j = 0; j < 4; ++j) { g[j] = *(const f32x4*)(A.in[I_NG] + (l_norm * 3 + i_norm) * DM + 256 * j + 4 * lane); bb[j] = *(const f32x4*)(A.in[I_NB] + (l_norm * 3 + i_norm) * DM + 256 * j + 4 * lane); }
;     }
;     bf16* X16 = (bf16*)(A.ws + WS_X16);
;     u32x2 un[4]; f32x4 fn[4];
;     int mi_cur = -1; f32x4 shv[4], sclv[4];
;     { const int row = bid * 8 + wave;
;       if (row < nrows) {
;           if (init) { const float* xin = row < M_LAT ? A.in[I_X] + (size_t)row * DM : A.in[I_CTX] + (size_t)(row - M_LAT) * DM;
; #pragma unroll
;               for (int j = 0; j < 4; ++j) fn[j] = *(const f32x4*)(xin + 256 * j + 4 * lane); }
;           else {
; #pragma unroll
;               for (int j = 0; j < 4; ++j) un[j] = *(const u32x2*)(X16 + (size_t)row * DM + 256 * j + 4 * lane); } } }
;     for (int row = bid * 8 + wave; row < nrows; row += G * 8) {
.LBB0_225:
	v_ashrrev_i32_e32 v116, 6, v152
	v_readlane_b32 s1, v253, 33
	v_readlane_b32 s4, v253, 35
	s_add_i32 s6, s4, 1
	s_waitcnt vmcnt(0)
	v_lshl_add_u32 v80, s1, 3, v116
	v_readlane_b32 s1, v253, 39
	v_readlane_b32 s5, v253, 36
	s_nop 0
	v_cmp_gt_i32_e32 vcc, s1, v80
	s_and_saveexec_b64 s[8:9], vcc
	s_cbranch_execz .LBB0_242
	v_ashrrev_i32_e32 v81, 31, v80
	v_readlane_b32 s4, v251, 45
	v_lshlrev_b64 v[82:83], 11, v[80:81]
	v_readlane_b32 s5, v251, 46
	v_lshlrev_b32_e32 v146, 3, v85
	v_readlane_b32 s16, v252, 54
	v_lshl_add_u64 v[32:33], s[4:5], 0, v[82:83]
	v_lshl_add_u64 v[32:33], v[32:33], 0, v[146:147]
	global_load_dwordx2 v[66:67], v[32:33], off
	global_load_dwordx2 v[72:73], v[32:33], off offset:512
	global_load_dwordx2 v[70:71], v[32:33], off offset:1024
	global_load_dwordx2 v[76:77], v[32:33], off offset:1536
	v_readlane_b32 s4, v253, 37
	v_readlane_b32 s5, v253, 38
	s_and_b64 s[4:5], s[4:5], exec
	s_cselect_b32 s7, s6, -1
	s_addk_i32 s0, 0x400
	s_ashr_i32 s1, s0, 31
	s_lshl_b64 s[0:1], s[0:1], 2
	v_readlane_b32 s28, v253, 2
	v_readlane_b32 s29, v253, 3
	s_add_u32 s4, s28, s0
	v_readlane_b32 s30, v253, 4
	s_addc_u32 s5, s29, s1
	v_readlane_b32 s31, v253, 5
	s_add_u32 s0, s30, s0
	v_readlane_b32 s14, v253, 34
	s_addc_u32 s1, s31, s1
	s_lshl_b32 s14, s14, 3
	v_readlane_b32 s17, v252, 55
	s_cmp_gt_i32 s7, -1
	v_readlane_b32 s18, v252, 56
	v_readlane_b32 s19, v252, 57
	v_lshlrev_b32_e32 v32, 4, v85
	v_mov_b32_e32 v33, v147
	s_cselect_b64 s[16:17], -1, 0
	v_cmp_eq_u32_e32 vcc, 0, v85
	v_lshl_add_u64 v[86:87], s[4:5], 0, v[32:33]
	v_lshl_add_u64 v[88:89], s[0:1], 0, v[32:33]
	s_and_b64 s[18:19], s[16:17], vcc
	v_add_u32_e32 v32, s14, v80
	s_cmp_lt_i32 s7, 0
	v_ashrrev_i32_e32 v33, 31, v32
	v_readlane_b32 s20, v252, 58
	v_readlane_b32 s21, v252, 59
	s_cselect_b64 s[0:1], -1, 0
	v_lshlrev_b64 v[90:91], 11, v[32:33]
	v_mov_b64_e32 v[32:33], 0x240000
	s_and_b64 s[20:21], s[2:3], s[0:1]
	v_lshl_add_u64 v[92:93], v[80:81], 3, v[32:33]
	v_lshlrev_b64 v[32:33], 12, v[80:81]
	v_readlane_b32 s0, v252, 27
	v_readlane_b32 s22, v252, 60
	v_readlane_b32 s23, v252, 61
	v_readlane_b32 s24, v252, 62
	v_readlane_b32 s25, v252, 63
	v_readlane_b32 s26, v253, 0
	v_readlane_b32 s27, v253, 1
	s_ashr_i32 s15, s14, 31
	v_lshl_or_b32 v32, v85, 4, v32
	v_readlane_b32 s1, v252, 28
	v_lshlrev_b32_e32 v84, 2, v85
	s_mul_hi_u32 s23, s7, 9
	s_mul_i32 s22, s7, 9
	v_or_b32_e32 v90, v90, v146
	s_lshl_b64 s[24:25], s[14:15], 11
	s_lshl_b64 s[26:27], s[14:15], 3
	v_or_b32_e32 v82, v82, v146
	v_lshl_add_u64 v[94:95], s[0:1], 0, v[32:33]
	s_lshl_b64 s[28:29], s[14:15], 12
	v_mov_b32_e32 v117, -1
	s_mov_b64 s[30:31], 0
	v_mov_b32_e32 v118, v80
	s_waitcnt vmcnt(0)
	s_branch .LBB0_229

; DI float hlo(unsigned u) { return (float)__builtin_bit_cast(f16x2_t, u).x; }
; DI float hhi(unsigned u) { return (float)__builtin_bit_cast(f16x2_t, u).y; }
; DI void lnmod_phase(const Args& A, LAS unsigned char* lds, int tid, int bid, int G, bool init, int l_norm, int i_norm, int l_mod, int i_mod, bool want_dt, int nrows, bool ctx_partial, const float* gprev, const float* bprev) {
;     ...
;     for (int row = bid * 8 + wave; row < nrows; row += G * 8) {
;         bf16* xout = X16 + (size_t)row * DM;
;         f32x4 v[4];
; #pragma unroll
;         for (int j = 0; j < 4; ++j) v[j] = init ? fn[j] : (f32x4){hlo(un[j].x), hhi(un[j].x), hlo(un[j].y), hhi(un[j].y)};
;         { const int rown = row + G * 8;
;           if (rown < nrows) {
;               if (init) { const float* xin = rown < M_LAT ? A.in[I_X] + (size_t)rown * DM : A.in[I_CTX] + (size_t)(rown - M_LAT) * DM;
; #pragma unroll
;                   for (int j = 0; j < 4; ++j) fn[j] = *(const f32x4*)(xin + 256 * j + 4 * lane); }
;               else {
; #pragma unroll
;                   for (int j = 0; j < 4; ++j) un[j] = *(const u32x2*)(X16 + (size_t)rown * DM + 256 * j + 4 * lane); } } }
.LBB0_228:
	v_lshl_add_u64 v[90:91], v[90:91], 0, s[24:25]
	v_lshl_add_u64 v[92:93], v[92:93], 0, s[26:27]
	v_lshl_add_u64 v[82:83], v[82:83], 0, s[24:25]
	v_lshl_add_u64 v[94:95], v[94:95], 0, s[28:29]
	v_mov_b32_e32 v118, v81
	v_mov_b32_e32 v66, v130
	v_mov_b32_e32 v67, v131
	v_mov_b32_e32 v72, v132
	v_mov_b32_e32 v73, v133
	v_mov_b32_e32 v70, v134
	v_mov_b32_e32 v71, v135
	v_mov_b32_e32 v76, v136
	v_mov_b32_e32 v77, v137
	s_andn2_b64 exec, exec, s[30:31]
	s_cbranch_execz .LBB0_242
.LBB0_229:
	v_add_u32_e32 v81, s14, v118
	v_readlane_b32 s0, v253, 39
	v_mov_b32_e32 v96, v66
	v_mov_b32_e32 v97, v67
	v_cmp_gt_i32_e32 vcc, s0, v81
	v_cmp_le_i32_e64 s[0:1], s0, v81
	v_mov_b32_e32 v98, v72
	v_mov_b32_e32 v99, v73
	v_mov_b32_e32 v100, v70
	v_mov_b32_e32 v101, v71
	v_mov_b32_e32 v102, v76
	v_mov_b32_e32 v103, v77
	s_and_saveexec_b64 s[4:5], vcc
	s_cbranch_execz .LBB0_231
	v_readlane_b32 s36, v253, 23
	v_readlane_b32 s38, v253, 25
	v_readlane_b32 s39, v253, 26
	v_readlane_b32 s37, v253, 24
	s_nop 0
	v_lshl_add_u64 v[64:65], s[38:39], 0, v[90:91]
	v_add_co_u32_e32 v64, vcc, 0x21200000, v64
	s_nop 1
	v_addc_co_u32_e32 v65, vcc, 0, v65, vcc
	global_load_dwordx2 v[96:97], v[64:65], off
	global_load_dwordx2 v[98:99], v[64:65], off offset:512
	global_load_dwordx2 v[100:101], v[64:65], off offset:1024
	global_load_dwordx2 v[102:103], v[64:65], off offset:1536

; DI void lnmod_phase(const Args& A, LAS unsigned char* lds, int tid, int bid, int G, bool init, int l_norm, int i_norm, int l_mod, int i_mod, bool want_dt, int nrows, bool ctx_partial, const float* gprev, const float* bprev) {
;     ...
;         if (l_mod >= 0) {
;             const int mi = row < M_LAT ? (row >> 12) : 8;
;             const float* mp = MOD + ((size_t)l_mod * 9 + mi) * 9216 + i_mod * 3072;
;             if (mi != mi_cur) { mi_cur = mi;
; #pragma unroll
;                 for (int j = 0; j < 4; ++j) { shv[j] = *(const f32x4*)(mp + 256 * j + 4 * lane); sclv[j] = *(const f32x4*)(mp + 1024 + 256 * j + 4 * lane) + 1.0f; } }
.LBB0_239:
	s_waitcnt vmcnt(0)
	v_mov_b32_e32 v130, v96
	v_mov_b32_e32 v131, v97
	v_mov_b32_e32 v132, v98
	v_mov_b32_e32 v133, v99
	v_mov_b32_e32 v134, v100
	v_mov_b32_e32 v135, v101
	v_mov_b32_e32 v136, v102
	v_mov_b32_e32 v137, v103
	s_andn2_b64 vcc, exec, s[16:17]
	s_cbranch_vccnz .LBB0_228
	v_min_i32_e32 v106, 0x8000, v118
	v_ashrrev_i32_e32 v106, 12, v106
	v_cmp_ne_u32_e32 vcc, v106, v117
	s_and_saveexec_b64 s[0:1], vcc
	s_cbranch_execz .LBB0_227
	v_readlane_b32 s36, v253, 23
	v_ashrrev_i32_e32 v107, 31, v106
	v_readlane_b32 s38, v253, 25
	v_readlane_b32 s39, v253, 26
	v_lshl_add_u64 v[32:33], s[22:23], 0, v[106:107]
	v_lshlrev_b32_e32 v146, 2, v84
	v_mov_b64_e32 v[34:35], s[38:39]
	v_mad_u64_u32 v[34:35], s[4:5], v32, s94, v[34:35]
	v_mad_i32_i24 v35, v33, s94, v35
	v_lshl_add_u64 v[32:33], v[34:35], 0, v[146:147]
	s_mov_b64 s[4:5], 0x1000
	v_lshl_add_u64 v[34:35], v[32:33], 0, s[4:5]
	global_load_dwordx4 v[48:51], v[34:35], off offset:1024
	global_load_dwordx4 v[52:55], v[34:35], off offset:2048
	s_movk_i32 s4, 0x1000
	v_add_co_u32_e32 v36, vcc, s4, v32
	v_mov_b32_e32 v117, v106
	s_nop 0
	v_addc_co_u32_e32 v37, vcc, 0, v33, vcc
	global_load_dwordx4 v[56:59], v[36:37], off
	global_load_dwordx4 v[60:63], v[34:35], off offset:3072
	global_load_dwordx4 v[44:47], v[32:33], off
	global_load_dwordx4 v[40:43], v[32:33], off offset:1024
	s_nop 0
	global_load_dwordx4 v[36:39], v[32:33], off offset:2048
	s_nop 0
	global_load_dwordx4 v[32:35], v[32:33], off offset:3072
	v_readlane_b32 s37, v253, 24
	s_waitcnt vmcnt(7)
	v_pk_add_f32 v[50:51], v[50:51], 1.0 op_sel_hi:[1,0]
	v_pk_add_f32 v[48:49], v[48:49], 1.0 op_sel_hi:[1,0]
	s_waitcnt vmcnt(6)
	v_pk_add_f32 v[54:55], v[54:55], 1.0 op_sel_hi:[1,0]
	v_pk_add_f32 v[52:53], v[52:53], 1.0 op_sel_hi:[1,0]
	s_waitcnt vmcnt(5)
	v_pk_add_f32 v[58:59], v[58:59], 1.0 op_sel_hi:[1,0]
	v_pk_add_f32 v[56:57], v[56:57], 1.0 op_sel_hi:[1,0]
	s_waitcnt vmcnt(4)
	v_pk_add_f32 v[62:63], v[62:63], 1.0 op_sel_hi:[1,0]
	v_pk_add_f32 v[60:61], v[60:61], 1.0 op_sel_hi:[1,0]
	s_branch .LBB0_227
